# P4: static s_setprio 1 for waves 4-7 over the attention phase
# speedup vs baseline: 1.0052x; 1.0052x over previous
.LBB0_916:
	s_load_dwordx2 s[0:1], s[62:63], 0xc8
	s_waitcnt lgkmcnt(0)
	s_cmp_lt_i32 s0, 5
	s_cselect_b64 s[0:1], -1, 0
	v_writelane_b32 v244, s0, 4
	s_nop 1
	v_writelane_b32 v244, s1, 5
	s_and_b64 s[0:1], s[0:1], s[6:7]
	s_andn2_b64 vcc, exec, s[0:1]
	s_cbranch_vccnz .LBB0_1192
	s_add_u32 s78, s34, 0x4600000
	s_addc_u32 s79, s35, 0
	s_add_u32 s0, s34, 0x5800000
	v_writelane_b32 v245, s0, 60
	s_addc_u32 s0, s35, 0
	v_writelane_b32 v245, s0, 62
	s_add_u32 s0, s34, 0x6a00000
	v_writelane_b32 v244, s0, 0
	s_addc_u32 s0, s35, 0
	s_add_u32 s76, s34, 0xc200000
	s_addc_u32 s77, s35, 0
	v_writelane_b32 v244, s0, 2
	s_add_u32 s0, s34, 0xdd00000
	v_writelane_b32 v245, s0, 58
	s_addc_u32 s0, s35, 0
	s_add_u32 s80, s34, 0xc000000
	s_addc_u32 s81, s35, 0
	s_add_u32 s54, s34, 0x1ad00000
	v_writelane_b32 v245, s0, 57
	s_addc_u32 s0, s35, 0
	s_add_u32 s84, s34, 0x1c00000
	s_addc_u32 s85, s35, 0
	s_add_u32 s86, s34, 0x2100000
	s_addc_u32 s87, s35, 0
	s_add_u32 s88, s34, 0x10100000
	v_writelane_b32 v244, s0, 3
	s_addc_u32 s89, s35, 0
	s_lshr_b32 s0, s96, 6
	s_cmpk_lt_i32 s96, 0x100
	s_cselect_b64 s[6:7], -1, 0
	s_add_u32 s92, s34, 0x3b700000
	s_addc_u32 s93, s35, 0
	s_add_u32 s94, s34, 0x16d00000
	s_addc_u32 s95, s35, 0
	s_mov_b32 s2, s96
	s_add_u32 s96, s34, 0xb700000
	v_readlane_b32 s36, v245, 19
	s_addc_u32 s97, s35, 0
	v_readlane_b32 s48, v245, 31
	v_readlane_b32 s49, v245, 32
	s_load_dword s3, s[62:63], 0xd0
	s_add_u32 s18, s34, 0x1b00000
	v_readlane_b32 s50, v245, 33
	v_readlane_b32 s51, v245, 34
	s_mov_b64 s[20:21], s[48:49]
	s_addc_u32 s19, s35, 0
	s_mov_b64 s[22:23], s[50:51]
	s_add_u32 s4, s22, 0x9ad8000
	v_writelane_b32 v244, s0, 6
	s_addc_u32 s5, s23, 0
	s_mov_b32 s0, s2
	v_readlane_b32 s37, v245, 20
	v_readlane_b32 s38, v245, 21
	v_readlane_b32 s39, v245, 22
	v_readlane_b32 s40, v245, 23
	v_readlane_b32 s41, v245, 24
	v_readlane_b32 s42, v245, 25
	v_readlane_b32 s43, v245, 26
	v_readlane_b32 s44, v245, 27
	v_readlane_b32 s45, v245, 28
	v_readlane_b32 s46, v245, 29
	v_readlane_b32 s47, v245, 30
	s_add_u32 s14, s22, 0x9ed8000
	v_writelane_b32 v245, s0, 39
	s_addc_u32 s15, s23, 0
	s_waitcnt lgkmcnt(0)
	s_lshl_b32 s16, s3, 2
	v_writelane_b32 v245, s1, 40
	s_lshl_b32 s0, s2, 2
	v_writelane_b32 v244, s0, 7
	s_add_u32 s20, s34, 0x6a30000
	v_mbcnt_lo_u32_b32 v217, -1, 0
	s_movk_i32 s91, 0x100
	s_addc_u32 s21, s35, 0
	s_mov_b32 s17, 0
	v_writelane_b32 v244, s6, 8
	s_movk_i32 s33, 0x600
	v_mov_b32_e32 v199, 0
	v_cndmask_b32_e64 v216, 0, 1, s[6:7]
	s_mov_b64 s[22:23], 0x40000
	s_mov_b32 s68, 0x40000
	s_movk_i32 s69, 0x2000
	s_movk_i32 s0, 0x4000
	s_movk_i32 s1, 0x250
	s_mov_b64 s[24:25], 0x2000
	s_mov_b64 s[26:27], 0x10000
	s_add_i32 s90, 0, 0x21400
	s_add_i32 s2, 0, 0x21000
	s_movk_i32 s82, 0x90
	s_movk_i32 s83, 0xffe0
	s_mov_b64 s[28:29], 0x20000
	s_movk_i32 s52, 0xd0
	v_mbcnt_hi_u32_b32 v218, -1, v217
	v_mov_b32_e32 v219, 0xf149f2ca
	v_writelane_b32 v244, s7, 9
	v_writelane_b32 v245, s54, 55
	v_readfirstlane_b32 s6, v0
	s_cmpk_lt_u32 s6, 0x100
	s_cbranch_scc1 .Lp4prio_skip
	s_setprio 1
.Lp4prio_skip:
	s_branch .LBB0_920

.LBB0_1191:
	s_setprio 0
	v_readlane_b32 s62, v245, 37
	v_readlane_b32 s63, v245, 38
	v_readlane_b32 s96, v245, 39
	v_readlane_b32 s97, v245, 40
